# P6 QG nt=16 tiles (last half round): K loop copy without the never-stored (.,1)-quadrant MFMAs
# speedup vs baseline: 1.0261x; 1.0073x over previous
.Lqg16_loop:
	v_add_u32_e32 v165, s56, v164
	ds_read_b128 v[170:173], v165
	ds_read_b128 v[174:177], v165 offset:1024
	ds_read_b128 v[178:181], v165 offset:2048
	ds_read_b128 v[182:185], v165 offset:3072
	v_add_u32_e32 v166, 0xc000, v151
	v_lshl_add_u64 v[194:195], s[76:77], 0, v[142:143]
	v_readfirstlane_b32 s24, v166
	v_add_u32_e32 v167, 0xe000, v151
	v_lshl_add_u64 v[168:169], v[194:195], 0, s[14:15]
	s_mov_b32 m0, s24
	v_lshl_add_u64 v[236:237], s[76:77], 0, v[144:145]
	v_readfirstlane_b32 s24, v167
	ds_read_b128 v[186:189], v153
	ds_read_b128 v[190:193], v153 offset:1024
	ds_read_b128 v[196:199], v152
	ds_read_b128 v[200:203], v152 offset:1024
	ds_read_b128 v[204:207], v150
	ds_read_b128 v[208:211], v150 offset:1024
	ds_read_b128 v[212:215], v149
	ds_read_b128 v[216:219], v149 offset:1024
	global_load_lds_dwordx4 v[168:169], off
	v_lshl_add_u64 v[168:169], v[236:237], 0, s[14:15]
	s_mov_b32 m0, s24
	s_nop 0
	global_load_lds_dwordx4 v[168:169], off
	s_waitcnt lgkmcnt(8)
	s_barrier
	s_waitcnt lgkmcnt(0)
	s_setprio 1
	s_waitcnt lgkmcnt(0)
	v_mfma_f32_16x16x32_bf16 v[124:127], v[170:173], v[186:189], v[124:127]
	v_mfma_f32_16x16x32_bf16 v[120:123], v[178:181], v[186:189], v[120:123]
	v_mfma_f32_16x16x32_bf16 v[116:119], v[170:173], v[196:199], v[116:119]
	v_mfma_f32_16x16x32_bf16 v[112:115], v[178:181], v[196:199], v[112:115]
	v_mfma_f32_16x16x32_bf16 v[108:111], v[170:173], v[204:207], v[108:111]
	v_mfma_f32_16x16x32_bf16 v[104:107], v[178:181], v[204:207], v[104:107]
	v_mfma_f32_16x16x32_bf16 v[100:103], v[170:173], v[212:215], v[100:103]
	v_mfma_f32_16x16x32_bf16 v[96:99], v[178:181], v[212:215], v[96:99]
	v_mfma_f32_16x16x32_bf16 v[124:127], v[174:177], v[190:193], v[124:127]
	v_mfma_f32_16x16x32_bf16 v[120:123], v[182:185], v[190:193], v[120:123]
	v_mfma_f32_16x16x32_bf16 v[116:119], v[174:177], v[200:203], v[116:119]
	v_mfma_f32_16x16x32_bf16 v[112:115], v[182:185], v[200:203], v[112:115]
	v_mfma_f32_16x16x32_bf16 v[108:111], v[174:177], v[208:211], v[108:111]
	v_mfma_f32_16x16x32_bf16 v[104:107], v[182:185], v[208:211], v[104:107]
	v_mfma_f32_16x16x32_bf16 v[100:103], v[174:177], v[216:219], v[100:103]
	v_mfma_f32_16x16x32_bf16 v[96:99], v[182:185], v[216:219], v[96:99]
	s_setprio 0
	s_barrier
	v_lshl_add_u64 v[240:241], s[76:77], 0, v[134:135]
	v_readfirstlane_b32 s24, v148
	v_add_u32_e32 v169, 0x2000, v148
	v_add_u32_e32 v168, s61, v164
	v_lshl_add_u64 v[238:239], v[240:241], 0, s[16:17]
	s_mov_b32 m0, s24
	v_lshl_add_u64 v[242:243], s[76:77], 0, v[136:137]
	v_readfirstlane_b32 s24, v169
	ds_read_b128 v[220:223], v168
	ds_read_b128 v[224:227], v168 offset:1024
	ds_read_b128 v[228:231], v168 offset:2048
	ds_read_b128 v[232:235], v168 offset:3072
	global_load_lds_dwordx4 v[238:239], off
	v_lshl_add_u64 v[238:239], v[242:243], 0, s[16:17]
	s_mov_b32 m0, s24
	s_nop 0
	global_load_lds_dwordx4 v[238:239], off
	s_barrier
	s_waitcnt lgkmcnt(0)
	s_setprio 1
	s_waitcnt lgkmcnt(0)
	s_setprio 0
	v_lshl_add_u64 v[244:245], s[76:77], 0, v[138:139]
	v_readfirstlane_b32 s24, v151
	v_lshl_add_u64 v[238:239], v[244:245], 0, s[18:19]
	s_mov_b32 m0, s24
	v_lshl_add_u64 v[246:247], s[76:77], 0, v[140:141]
	v_readfirstlane_b32 s24, v154
	s_barrier
	ds_read_b128 v[186:189], v153 offset:16384
	ds_read_b128 v[190:193], v153 offset:17408
	ds_read_b128 v[196:199], v152 offset:16384
	ds_read_b128 v[200:203], v152 offset:17408
	ds_read_b128 v[204:207], v150 offset:16384
	ds_read_b128 v[208:211], v150 offset:17408
	ds_read_b128 v[212:215], v149 offset:16384
	ds_read_b128 v[216:219], v149 offset:17408
	global_load_lds_dwordx4 v[238:239], off
	v_lshl_add_u64 v[238:239], v[246:247], 0, s[18:19]
	s_mov_b32 m0, s24
	s_nop 0
	global_load_lds_dwordx4 v[238:239], off
	s_barrier
	s_waitcnt lgkmcnt(0)
	s_setprio 1
	s_waitcnt lgkmcnt(0)
	v_mfma_f32_16x16x32_bf16 v[60:63], v[170:173], v[186:189], v[60:63]
	v_mfma_f32_16x16x32_bf16 v[56:59], v[178:181], v[186:189], v[56:59]
	v_mfma_f32_16x16x32_bf16 v[52:55], v[170:173], v[196:199], v[52:55]
	v_mfma_f32_16x16x32_bf16 v[48:51], v[178:181], v[196:199], v[48:51]
	v_mfma_f32_16x16x32_bf16 v[44:47], v[170:173], v[204:207], v[44:47]
	v_mfma_f32_16x16x32_bf16 v[40:43], v[178:181], v[204:207], v[40:43]
	v_mfma_f32_16x16x32_bf16 v[36:39], v[170:173], v[212:215], v[36:39]
	v_mfma_f32_16x16x32_bf16 v[32:35], v[178:181], v[212:215], v[32:35]
	v_mfma_f32_16x16x32_bf16 v[60:63], v[174:177], v[190:193], v[60:63]
	v_mfma_f32_16x16x32_bf16 v[56:59], v[182:185], v[190:193], v[56:59]
	v_mfma_f32_16x16x32_bf16 v[52:55], v[174:177], v[200:203], v[52:55]
	v_mfma_f32_16x16x32_bf16 v[48:51], v[182:185], v[200:203], v[48:51]
	v_mfma_f32_16x16x32_bf16 v[44:47], v[174:177], v[208:211], v[44:47]
	v_mfma_f32_16x16x32_bf16 v[40:43], v[182:185], v[208:211], v[40:43]
	v_mfma_f32_16x16x32_bf16 v[36:39], v[174:177], v[216:219], v[36:39]
	v_mfma_f32_16x16x32_bf16 v[32:35], v[182:185], v[216:219], v[32:35]
	s_setprio 0
	s_barrier
	v_readfirstlane_b32 s24, v155
	v_add_u32_e32 v169, 0x2000, v155
	v_lshl_add_u64 v[170:171], v[240:241], 0, s[20:21]
	s_mov_b32 m0, s24
	v_readfirstlane_b32 s24, v169
	global_load_lds_dwordx4 v[170:171], off
	v_lshl_add_u64 v[170:171], v[242:243], 0, s[20:21]
	s_mov_b32 m0, s24
	s_nop 0
	global_load_lds_dwordx4 v[170:171], off
	s_waitcnt vmcnt(6)
	s_barrier
	s_setprio 1
	s_setprio 0
	v_add_u32_e32 v169, s62, v164
	s_barrier
	ds_read_b128 v[172:175], v169
	ds_read_b128 v[176:179], v169 offset:1024
	ds_read_b128 v[180:183], v169 offset:2048
	ds_read_b128 v[184:187], v169 offset:3072
	v_readfirstlane_b32 s24, v156
	v_lshl_add_u64 v[170:171], v[194:195], 0, s[18:19]
	s_mov_b32 m0, s24
	v_readfirstlane_b32 s24, v157
	ds_read_b128 v[188:191], v153 offset:32768
	ds_read_b128 v[196:199], v153 offset:33792
	ds_read_b128 v[200:203], v152 offset:32768
	ds_read_b128 v[204:207], v152 offset:33792
	ds_read_b128 v[208:211], v150 offset:32768
	ds_read_b128 v[212:215], v150 offset:33792
	ds_read_b128 v[216:219], v149 offset:32768
	ds_read_b128 v[220:223], v149 offset:33792
	global_load_lds_dwordx4 v[170:171], off
	v_lshl_add_u64 v[170:171], v[236:237], 0, s[18:19]
	s_mov_b32 m0, s24
	s_nop 0
	global_load_lds_dwordx4 v[170:171], off
	s_waitcnt lgkmcnt(8)
	s_barrier
	s_waitcnt lgkmcnt(0)
	s_setprio 1
	s_waitcnt lgkmcnt(0)
	v_mfma_f32_16x16x32_bf16 v[124:127], v[172:175], v[188:191], v[124:127]
	v_mfma_f32_16x16x32_bf16 v[120:123], v[180:183], v[188:191], v[120:123]
	v_mfma_f32_16x16x32_bf16 v[116:119], v[172:175], v[200:203], v[116:119]
	v_mfma_f32_16x16x32_bf16 v[112:115], v[180:183], v[200:203], v[112:115]
	v_mfma_f32_16x16x32_bf16 v[108:111], v[172:175], v[208:211], v[108:111]
	v_mfma_f32_16x16x32_bf16 v[104:107], v[180:183], v[208:211], v[104:107]
	v_mfma_f32_16x16x32_bf16 v[100:103], v[172:175], v[216:219], v[100:103]
	v_mfma_f32_16x16x32_bf16 v[96:99], v[180:183], v[216:219], v[96:99]
	v_mfma_f32_16x16x32_bf16 v[124:127], v[176:179], v[196:199], v[124:127]
	v_mfma_f32_16x16x32_bf16 v[120:123], v[184:187], v[196:199], v[120:123]
	v_mfma_f32_16x16x32_bf16 v[116:119], v[176:179], v[204:207], v[116:119]
	v_mfma_f32_16x16x32_bf16 v[112:115], v[184:187], v[204:207], v[112:115]
	v_mfma_f32_16x16x32_bf16 v[108:111], v[176:179], v[212:215], v[108:111]
	v_mfma_f32_16x16x32_bf16 v[104:107], v[184:187], v[212:215], v[104:107]
	v_mfma_f32_16x16x32_bf16 v[100:103], v[176:179], v[220:223], v[100:103]
	v_mfma_f32_16x16x32_bf16 v[96:99], v[184:187], v[220:223], v[96:99]
	s_setprio 0
	s_barrier
	v_readfirstlane_b32 s24, v158
	v_add_u32_e32 v170, s63, v164
	v_lshl_add_u64 v[192:193], v[240:241], 0, s[22:23]
	s_mov_b32 m0, s24
	v_readfirstlane_b32 s24, v159
	ds_read_b128 v[224:227], v170
	ds_read_b128 v[228:231], v170 offset:1024
	ds_read_b128 v[232:235], v170 offset:2048
	ds_read_b128 v[236:239], v170 offset:3072
	global_load_lds_dwordx4 v[192:193], off
	v_lshl_add_u64 v[192:193], v[242:243], 0, s[22:23]
	s_mov_b32 m0, s24
	s_nop 0
	global_load_lds_dwordx4 v[192:193], off
	s_barrier
	s_waitcnt lgkmcnt(0)
	s_setprio 1
	s_waitcnt lgkmcnt(0)
	s_setprio 0
	v_readfirstlane_b32 s24, v160
	v_lshl_add_u64 v[192:193], v[244:245], 0, s[36:37]
	s_mov_b32 m0, s24
	v_readfirstlane_b32 s24, v161
	s_barrier
	ds_read_b128 v[188:191], v153 offset:49152
	ds_read_b128 v[196:199], v153 offset:50176
	ds_read_b128 v[200:203], v152 offset:49152
	ds_read_b128 v[204:207], v152 offset:50176
	ds_read_b128 v[208:211], v150 offset:49152
	ds_read_b128 v[212:215], v150 offset:50176
	ds_read_b128 v[216:219], v149 offset:49152
	ds_read_b128 v[220:223], v149 offset:50176
	global_load_lds_dwordx4 v[192:193], off
	v_lshl_add_u64 v[192:193], v[246:247], 0, s[36:37]
	s_mov_b32 m0, s24
	s_nop 0
	global_load_lds_dwordx4 v[192:193], off
	s_barrier
	s_waitcnt lgkmcnt(0)
	s_setprio 1
	s_waitcnt lgkmcnt(0)
	v_mfma_f32_16x16x32_bf16 v[60:63], v[172:175], v[188:191], v[60:63]
	v_mfma_f32_16x16x32_bf16 v[56:59], v[180:183], v[188:191], v[56:59]
	v_mfma_f32_16x16x32_bf16 v[52:55], v[172:175], v[200:203], v[52:55]
	v_mfma_f32_16x16x32_bf16 v[48:51], v[180:183], v[200:203], v[48:51]
	v_mfma_f32_16x16x32_bf16 v[44:47], v[172:175], v[208:211], v[44:47]
	v_mfma_f32_16x16x32_bf16 v[40:43], v[180:183], v[208:211], v[40:43]
	v_mfma_f32_16x16x32_bf16 v[36:39], v[172:175], v[216:219], v[36:39]
	v_mfma_f32_16x16x32_bf16 v[32:35], v[180:183], v[216:219], v[32:35]
	v_mfma_f32_16x16x32_bf16 v[60:63], v[176:179], v[196:199], v[60:63]
	v_mfma_f32_16x16x32_bf16 v[56:59], v[184:187], v[196:199], v[56:59]
	v_mfma_f32_16x16x32_bf16 v[52:55], v[176:179], v[204:207], v[52:55]
	v_mfma_f32_16x16x32_bf16 v[48:51], v[184:187], v[204:207], v[48:51]
	v_mfma_f32_16x16x32_bf16 v[44:47], v[176:179], v[212:215], v[44:47]
	v_mfma_f32_16x16x32_bf16 v[40:43], v[184:187], v[212:215], v[40:43]
	v_mfma_f32_16x16x32_bf16 v[36:39], v[176:179], v[220:223], v[36:39]
	v_mfma_f32_16x16x32_bf16 v[32:35], v[184:187], v[220:223], v[32:35]
	s_setprio 0
	s_barrier
	v_readfirstlane_b32 s24, v162
	v_lshl_add_u64 v[172:173], v[240:241], 0, s[38:39]
	s_mov_b32 m0, s24
	v_readfirstlane_b32 s24, v163
	global_load_lds_dwordx4 v[172:173], off
	v_lshl_add_u64 v[172:173], v[242:243], 0, s[38:39]
	s_mov_b32 m0, s24
	s_nop 0
	global_load_lds_dwordx4 v[172:173], off
	s_waitcnt vmcnt(6)
	s_barrier
	s_setprio 1
	s_setprio 0
	s_add_i32 s1, s1, 2
	v_lshl_add_u64 v[134:135], v[134:135], 0, s[40:41]
	v_lshl_add_u64 v[136:137], v[136:137], 0, s[40:41]
	v_lshl_add_u64 v[138:139], v[138:139], 0, s[40:41]
	v_lshl_add_u64 v[140:141], v[140:141], 0, s[40:41]
	v_lshl_add_u64 v[142:143], v[142:143], 0, s[40:41]
	s_cmp_lt_u32 s1, 28
	v_lshl_add_u64 v[144:145], v[144:145], 0, s[40:41]
	s_barrier
	s_cbranch_scc1 .Lqg16_loop
	s_branch .Lqg16_tail

.LBB0_634:
	s_add_i32 s28, 0, 0x18000
	v_add_u32_e32 v158, s28, v24
	v_add_u32_e32 v159, 0x2000, v158
	v_readfirstlane_b32 s28, v158
	v_lshl_add_u64 v[8:9], v[8:9], 0, s[12:13]
	s_mov_b32 m0, s28
	v_readfirstlane_b32 s28, v159
	v_add_u32_e32 v160, 0x8000, v151
	s_waitcnt vmcnt(4)
	s_barrier
	global_load_lds_dwordx4 v[8:9], off
	v_lshl_add_u64 v[8:9], v[10:11], 0, s[12:13]
	s_mov_b32 m0, s28
	v_readfirstlane_b32 s28, v160
	v_add_u32_e32 v161, 0xa000, v151
	global_load_lds_dwordx4 v[8:9], off
	v_lshl_add_u64 v[8:9], v[12:13], 0, s[12:13]
	s_mov_b32 m0, s28
	v_readfirstlane_b32 s28, v161
	global_load_lds_dwordx4 v[8:9], off
	s_mov_b32 m0, s28
	s_add_i32 s28, 0, 0x1c000
	v_add_u32_e32 v162, s28, v24
	v_lshl_add_u64 v[8:9], v[14:15], 0, s[12:13]
	v_readfirstlane_b32 s28, v162
	v_add_u32_e32 v163, 0x2000, v162
	global_load_lds_dwordx4 v[8:9], off
	v_lshl_add_u64 v[8:9], v[16:17], 0, s[12:13]
	s_mov_b32 m0, s28
	v_readfirstlane_b32 s28, v163
	global_load_lds_dwordx4 v[8:9], off
	v_lshl_add_u64 v[8:9], v[18:19], 0, s[12:13]
	s_mov_b32 m0, s28
	s_lshl_b32 s1, s66, 1
	global_load_lds_dwordx4 v[8:9], off
	v_and_b32_e32 v147, 15, v128
	s_and_b32 s1, s1, 0xfffff800
	v_lshlrev_b32_e32 v10, 2, v128
	s_lshl_b32 s25, s25, 8
	v_and_b32_e32 v8, 48, v128
	v_lshlrev_b32_e32 v9, 6, v147
	v_and_b32_e32 v10, 32, v10
	s_add_i32 s28, s1, s25
	v_bitop3_b32 v164, v9, v10, v8 bitop3:0x36
	v_or_b32_e32 v9, s27, v147
	s_ashr_i32 s29, s28, 31
	v_lshlrev_b32_e32 v10, 6, v9
	v_lshlrev_b32_e32 v9, 2, v9
	s_lshl_b64 s[28:29], s[28:29], 12
	s_and_b32 s33, s67, 0x1f00
	v_and_b32_e32 v10, 0x3c0, v10
	v_and_b32_e32 v9, 32, v9
	v_readlane_b32 s26, v253, 6
	v_lshl_add_u64 v[2:3], s[28:29], 0, v[2:3]
	v_bitop3_b32 v10, v10, v9, v8 bitop3:0x36
	v_or_b32_e32 v9, s26, v147
	v_lshl_add_u64 v[134:135], v[2:3], 0, v[0:1]
	v_lshl_add_u64 v[2:3], s[28:29], 0, v[6:7]
	s_add_i32 s33, s33, s24
	v_lshlrev_b32_e32 v11, 6, v9
	v_lshlrev_b32_e32 v9, 2, v9
	v_lshl_add_u64 v[136:137], v[2:3], 0, v[4:5]
	v_add3_u32 v2, v21, s33, v20
	v_and_b32_e32 v11, 0x3c0, v11
	v_and_b32_e32 v9, 32, v9
	v_readlane_b32 s26, v253, 7
	v_ashrrev_i32_e32 v3, 31, v2
	v_bitop3_b32 v11, v11, v9, v8 bitop3:0x36
	v_or_b32_e32 v9, s26, v147
	v_lshlrev_b64 v[6:7], 12, v[2:3]
	v_add_u32_e32 v2, 0x80, v2
	v_lshlrev_b32_e32 v12, 6, v9
	v_lshlrev_b32_e32 v9, 2, v9
	v_ashrrev_i32_e32 v3, 31, v2
	v_and_b32_e32 v12, 0x3c0, v12
	v_and_b32_e32 v9, 32, v9
	v_readlane_b32 s26, v253, 11
	v_lshl_add_u64 v[138:139], v[6:7], 0, v[0:1]
	v_add3_u32 v6, v23, s33, v22
	v_lshlrev_b64 v[2:3], 12, v[2:3]
	v_bitop3_b32 v12, v12, v9, v8 bitop3:0x36
	v_or_b32_e32 v9, s26, v147
	v_lshl_add_u64 v[142:143], v[2:3], 0, v[0:1]
	v_add_u32_e32 v0, 0x80, v6
	v_lshlrev_b32_e32 v13, 6, v9
	v_lshlrev_b32_e32 v9, 2, v9
	v_ashrrev_i32_e32 v1, 31, v0
	s_waitcnt vmcnt(6)
	v_and_b32_e32 v13, 0x3c0, v13
	v_and_b32_e32 v9, 32, v9
	v_ashrrev_i32_e32 v7, 31, v6
	v_lshlrev_b64 v[0:1], 12, v[0:1]
	v_bitop3_b32 v13, v13, v9, v8 bitop3:0x36
	v_lshlrev_b64 v[8:9], 12, v[6:7]
	v_lshl_add_u64 v[144:145], v[0:1], 0, v[4:5]
	v_mov_b32_e32 v0, 0
	v_lshl_add_u64 v[140:141], v[8:9], 0, v[4:5]
	s_mov_b32 s1, -2
	v_add_u32_e32 v153, s57, v10
	v_add_u32_e32 v152, s58, v11
	v_add_u32_e32 v150, s59, v12
	v_add_u32_e32 v149, s60, v13
	v_mov_b32_e32 v1, v0
	v_mov_b32_e32 v2, v0
	v_mov_b32_e32 v3, v0
	v_mov_b32_e32 v4, v0
	v_mov_b32_e32 v5, v0
	v_mov_b32_e32 v6, v0
	v_mov_b32_e32 v7, v0
	v_mov_b32_e32 v8, v0
	v_mov_b32_e32 v9, v0
	v_mov_b32_e32 v10, v0
	v_mov_b32_e32 v11, v0
	v_mov_b32_e32 v12, v0
	v_mov_b32_e32 v13, v0
	v_mov_b32_e32 v14, v0
	v_mov_b32_e32 v15, v0
	v_mov_b32_e32 v16, v0
	v_mov_b32_e32 v17, v0
	v_mov_b32_e32 v18, v0
	v_mov_b32_e32 v19, v0
	v_mov_b32_e32 v20, v0
	v_mov_b32_e32 v21, v0
	v_mov_b32_e32 v22, v0
	v_mov_b32_e32 v23, v0
	v_mov_b32_e32 v24, v0
	v_mov_b32_e32 v25, v0
	v_mov_b32_e32 v26, v0
	v_mov_b32_e32 v27, v0
	v_mov_b32_e32 v28, v0
	v_mov_b32_e32 v29, v0
	v_mov_b32_e32 v30, v0
	v_mov_b32_e32 v31, v0
	v_mov_b32_e32 v32, v0
	v_mov_b32_e32 v33, v0
	v_mov_b32_e32 v34, v0
	v_mov_b32_e32 v35, v0
	v_mov_b32_e32 v36, v0
	v_mov_b32_e32 v37, v0
	v_mov_b32_e32 v38, v0
	v_mov_b32_e32 v39, v0
	v_mov_b32_e32 v40, v0
	v_mov_b32_e32 v41, v0
	v_mov_b32_e32 v42, v0
	v_mov_b32_e32 v43, v0
	v_mov_b32_e32 v44, v0
	v_mov_b32_e32 v45, v0
	v_mov_b32_e32 v46, v0
	v_mov_b32_e32 v47, v0
	v_mov_b32_e32 v48, v0
	v_mov_b32_e32 v49, v0
	v_mov_b32_e32 v50, v0
	v_mov_b32_e32 v51, v0
	v_mov_b32_e32 v52, v0
	v_mov_b32_e32 v53, v0
	v_mov_b32_e32 v54, v0
	v_mov_b32_e32 v55, v0
	v_mov_b32_e32 v56, v0
	v_mov_b32_e32 v57, v0
	v_mov_b32_e32 v58, v0
	v_mov_b32_e32 v59, v0
	v_mov_b32_e32 v60, v0
	v_mov_b32_e32 v61, v0
	v_mov_b32_e32 v62, v0
	v_mov_b32_e32 v63, v0
	v_mov_b32_e32 v64, v0
	v_mov_b32_e32 v65, v0
	v_mov_b32_e32 v66, v0
	v_mov_b32_e32 v67, v0
	v_mov_b32_e32 v68, v0
	v_mov_b32_e32 v69, v0
	v_mov_b32_e32 v70, v0
	v_mov_b32_e32 v71, v0
	v_mov_b32_e32 v72, v0
	v_mov_b32_e32 v73, v0
	v_mov_b32_e32 v74, v0
	v_mov_b32_e32 v75, v0
	v_mov_b32_e32 v76, v0
	v_mov_b32_e32 v77, v0
	v_mov_b32_e32 v78, v0
	v_mov_b32_e32 v79, v0
	v_mov_b32_e32 v80, v0
	v_mov_b32_e32 v81, v0
	v_mov_b32_e32 v82, v0
	v_mov_b32_e32 v83, v0
	v_mov_b32_e32 v84, v0
	v_mov_b32_e32 v85, v0
	v_mov_b32_e32 v86, v0
	v_mov_b32_e32 v87, v0
	v_mov_b32_e32 v88, v0
	v_mov_b32_e32 v89, v0
	v_mov_b32_e32 v90, v0
	v_mov_b32_e32 v91, v0
	v_mov_b32_e32 v92, v0
	v_mov_b32_e32 v93, v0
	v_mov_b32_e32 v94, v0
	v_mov_b32_e32 v95, v0
	v_mov_b32_e32 v96, v0
	v_mov_b32_e32 v97, v0
	v_mov_b32_e32 v98, v0
	v_mov_b32_e32 v99, v0
	v_mov_b32_e32 v100, v0
	v_mov_b32_e32 v101, v0
	v_mov_b32_e32 v102, v0
	v_mov_b32_e32 v103, v0
	v_mov_b32_e32 v104, v0
	v_mov_b32_e32 v105, v0
	v_mov_b32_e32 v106, v0
	v_mov_b32_e32 v107, v0
	v_mov_b32_e32 v108, v0
	v_mov_b32_e32 v109, v0
	v_mov_b32_e32 v110, v0
	v_mov_b32_e32 v111, v0
	v_mov_b32_e32 v112, v0
	v_mov_b32_e32 v113, v0
	v_mov_b32_e32 v114, v0
	v_mov_b32_e32 v115, v0
	v_mov_b32_e32 v116, v0
	v_mov_b32_e32 v117, v0
	v_mov_b32_e32 v118, v0
	v_mov_b32_e32 v119, v0
	v_mov_b32_e32 v120, v0
	v_mov_b32_e32 v121, v0
	v_mov_b32_e32 v122, v0
	v_mov_b32_e32 v123, v0
	v_mov_b32_e32 v124, v0
	v_mov_b32_e32 v125, v0
	v_mov_b32_e32 v126, v0
	v_mov_b32_e32 v127, v0
	s_barrier
	s_cmpk_ge_i32 s75, 0xe00
	s_cbranch_scc1 .Lqg16_loop

.Lqg16_tail:
	v_readfirstlane_b32 s1, v166
	v_lshl_add_u64 v[130:131], v[130:131], 0, s[42:43]
	s_mov_b32 m0, s1
	v_readfirstlane_b32 s1, v167
	ds_read_b128 v[134:137], v165
	ds_read_b128 v[138:141], v165 offset:1024
	ds_read_b128 v[142:145], v165 offset:2048
	ds_read_b128 v[154:157], v165 offset:3072
	ds_read_b128 v[158:161], v153
	ds_read_b128 v[162:165], v153 offset:1024
	ds_read_b128 v[172:175], v152
	ds_read_b128 v[176:179], v152 offset:1024
	ds_read_b128 v[180:183], v150
	ds_read_b128 v[184:187], v150 offset:1024
	ds_read_b128 v[188:191], v149
	ds_read_b128 v[196:199], v149 offset:1024
	global_load_lds_dwordx4 v[130:131], off
	v_lshl_add_u64 v[130:131], v[132:133], 0, s[42:43]
	s_mov_b32 m0, s1
	s_nop 0
	global_load_lds_dwordx4 v[130:131], off
	s_barrier
	s_waitcnt lgkmcnt(0)
	s_setprio 1
	s_waitcnt lgkmcnt(0)
	v_mfma_f32_16x16x32_bf16 v[124:127], v[134:137], v[158:161], v[124:127]
	v_mfma_f32_16x16x32_bf16 v[116:119], v[134:137], v[172:175], v[116:119]
	v_mfma_f32_16x16x32_bf16 v[108:111], v[134:137], v[180:183], v[108:111]
	v_mfma_f32_16x16x32_bf16 v[100:103], v[134:137], v[188:191], v[100:103]
	v_mfma_f32_16x16x32_bf16 v[124:127], v[138:141], v[162:165], v[124:127]
	v_mfma_f32_16x16x32_bf16 v[120:123], v[142:145], v[158:161], v[120:123]
	v_mfma_f32_16x16x32_bf16 v[116:119], v[138:141], v[176:179], v[116:119]
	v_mfma_f32_16x16x32_bf16 v[112:115], v[142:145], v[172:175], v[112:115]
	v_mfma_f32_16x16x32_bf16 v[108:111], v[138:141], v[184:187], v[108:111]
	v_mfma_f32_16x16x32_bf16 v[104:107], v[142:145], v[180:183], v[104:107]
	v_mfma_f32_16x16x32_bf16 v[100:103], v[138:141], v[196:199], v[100:103]
	v_mfma_f32_16x16x32_bf16 v[96:99], v[142:145], v[188:191], v[96:99]
	v_mfma_f32_16x16x32_bf16 v[130:133], v[154:157], v[162:165], v[120:123]
	v_mfma_f32_16x16x32_bf16 v[200:203], v[154:157], v[176:179], v[112:115]
	v_mfma_f32_16x16x32_bf16 v[204:207], v[154:157], v[184:187], v[104:107]
	v_mfma_f32_16x16x32_bf16 v[208:211], v[154:157], v[196:199], v[96:99]
	s_setprio 0
	s_barrier
	s_nop 1
	ds_read_b128 v[96:99], v168
	ds_read_b128 v[104:107], v168 offset:1024
	ds_read_b128 v[112:115], v168 offset:2048
	ds_read_b128 v[120:123], v168 offset:3072
	s_barrier
	s_waitcnt lgkmcnt(0)
	s_setprio 1
	s_waitcnt lgkmcnt(0)
	v_mfma_f32_16x16x32_bf16 v[92:95], v[96:99], v[158:161], v[92:95]
	v_mfma_f32_16x16x32_bf16 v[84:87], v[96:99], v[172:175], v[84:87]
	v_mfma_f32_16x16x32_bf16 v[76:79], v[96:99], v[180:183], v[76:79]
	v_mfma_f32_16x16x32_bf16 v[68:71], v[96:99], v[188:191], v[68:71]
	v_mfma_f32_16x16x32_bf16 v[92:95], v[104:107], v[162:165], v[92:95]
	v_mfma_f32_16x16x32_bf16 v[88:91], v[112:115], v[158:161], v[88:91]
	v_mfma_f32_16x16x32_bf16 v[84:87], v[104:107], v[176:179], v[84:87]
	v_mfma_f32_16x16x32_bf16 v[80:83], v[112:115], v[172:175], v[80:83]
	v_mfma_f32_16x16x32_bf16 v[76:79], v[104:107], v[184:187], v[76:79]
	v_mfma_f32_16x16x32_bf16 v[72:75], v[112:115], v[180:183], v[72:75]
	v_mfma_f32_16x16x32_bf16 v[68:71], v[104:107], v[196:199], v[68:71]
	v_mfma_f32_16x16x32_bf16 v[64:67], v[112:115], v[188:191], v[64:67]
	v_mfma_f32_16x16x32_bf16 v[158:161], v[120:123], v[162:165], v[88:91]
	v_mfma_f32_16x16x32_bf16 v[162:165], v[120:123], v[176:179], v[80:83]
	v_mfma_f32_16x16x32_bf16 v[172:175], v[120:123], v[184:187], v[72:75]
	v_mfma_f32_16x16x32_bf16 v[176:179], v[120:123], v[196:199], v[64:67]
	s_setprio 0
	s_barrier
	s_nop 1
	ds_read_b128 v[64:67], v153 offset:16384
	ds_read_b128 v[72:75], v153 offset:17408
	ds_read_b128 v[80:83], v152 offset:16384
	ds_read_b128 v[88:91], v152 offset:17408
	ds_read_b128 v[180:183], v150 offset:16384
	ds_read_b128 v[184:187], v150 offset:17408
	ds_read_b128 v[188:191], v149 offset:16384
	ds_read_b128 v[196:199], v149 offset:17408
	s_waitcnt vmcnt(4)
	s_barrier
	s_waitcnt lgkmcnt(0)
	s_setprio 1
	s_waitcnt lgkmcnt(0)
	v_mfma_f32_16x16x32_bf16 v[60:63], v[134:137], v[64:67], v[60:63]
	v_mfma_f32_16x16x32_bf16 v[52:55], v[134:137], v[80:83], v[52:55]
	v_mfma_f32_16x16x32_bf16 v[44:47], v[134:137], v[180:183], v[44:47]
	v_mfma_f32_16x16x32_bf16 v[36:39], v[134:137], v[188:191], v[36:39]
	v_mfma_f32_16x16x32_bf16 v[60:63], v[138:141], v[72:75], v[60:63]
	v_mfma_f32_16x16x32_bf16 v[56:59], v[142:145], v[64:67], v[56:59]
	v_mfma_f32_16x16x32_bf16 v[52:55], v[138:141], v[88:91], v[52:55]
	v_mfma_f32_16x16x32_bf16 v[48:51], v[142:145], v[80:83], v[48:51]
	v_mfma_f32_16x16x32_bf16 v[44:47], v[138:141], v[184:187], v[44:47]
	v_mfma_f32_16x16x32_bf16 v[40:43], v[142:145], v[180:183], v[40:43]
	v_mfma_f32_16x16x32_bf16 v[36:39], v[138:141], v[196:199], v[36:39]
	v_mfma_f32_16x16x32_bf16 v[32:35], v[142:145], v[188:191], v[32:35]
	v_mfma_f32_16x16x32_bf16 v[212:215], v[154:157], v[72:75], v[56:59]
	v_mfma_f32_16x16x32_bf16 v[216:219], v[154:157], v[88:91], v[48:51]
	v_mfma_f32_16x16x32_bf16 v[220:223], v[154:157], v[184:187], v[40:43]
	v_mfma_f32_16x16x32_bf16 v[134:137], v[154:157], v[196:199], v[32:35]
	s_setprio 0
	s_setprio 1
	v_mfma_f32_16x16x32_bf16 v[28:31], v[96:99], v[64:67], v[28:31]
	v_mfma_f32_16x16x32_bf16 v[20:23], v[96:99], v[80:83], v[20:23]
	v_mfma_f32_16x16x32_bf16 v[12:15], v[96:99], v[180:183], v[12:15]
	v_mfma_f32_16x16x32_bf16 v[4:7], v[96:99], v[188:191], v[4:7]
	v_mfma_f32_16x16x32_bf16 v[28:31], v[104:107], v[72:75], v[28:31]
	v_mfma_f32_16x16x32_bf16 v[24:27], v[112:115], v[64:67], v[24:27]
	v_mfma_f32_16x16x32_bf16 v[20:23], v[104:107], v[88:91], v[20:23]
	v_mfma_f32_16x16x32_bf16 v[16:19], v[112:115], v[80:83], v[16:19]
	v_mfma_f32_16x16x32_bf16 v[12:15], v[104:107], v[184:187], v[12:15]
	v_mfma_f32_16x16x32_bf16 v[8:11], v[112:115], v[180:183], v[8:11]
	v_mfma_f32_16x16x32_bf16 v[4:7], v[104:107], v[196:199], v[4:7]
	v_mfma_f32_16x16x32_bf16 v[0:3], v[112:115], v[188:191], v[0:3]
	v_mfma_f32_16x16x32_bf16 v[138:141], v[120:123], v[72:75], v[24:27]
	v_mfma_f32_16x16x32_bf16 v[142:145], v[120:123], v[88:91], v[16:19]
	v_mfma_f32_16x16x32_bf16 v[154:157], v[120:123], v[184:187], v[8:11]
	v_mfma_f32_16x16x32_bf16 v[180:183], v[120:123], v[196:199], v[0:3]
	s_setprio 0
	s_barrier
	s_nop 1
	ds_read_b128 v[0:3], v169
	ds_read_b128 v[8:11], v169 offset:1024
	ds_read_b128 v[16:19], v169 offset:2048
	ds_read_b128 v[24:27], v169 offset:3072
	ds_read_b128 v[32:35], v153 offset:32768
	ds_read_b128 v[40:43], v153 offset:33792
	ds_read_b128 v[48:51], v152 offset:32768
	ds_read_b128 v[56:59], v152 offset:33792
	ds_read_b128 v[64:67], v150 offset:32768
	ds_read_b128 v[166:169], v150 offset:33792
	ds_read_b128 v[184:187], v149 offset:32768
	ds_read_b128 v[188:191], v149 offset:33792
	s_waitcnt vmcnt(2)
	s_barrier
	s_waitcnt lgkmcnt(0)
	s_setprio 1
	s_waitcnt lgkmcnt(0)
	v_mfma_f32_16x16x32_bf16 v[72:75], v[0:3], v[32:35], v[124:127]
	v_mfma_f32_16x16x32_bf16 v[120:123], v[8:11], v[40:43], v[72:75]
	v_mfma_f32_16x16x32_bf16 v[72:75], v[16:19], v[32:35], v[130:133]
	v_mfma_f32_16x16x32_bf16 v[124:127], v[24:27], v[40:43], v[72:75]
	v_mfma_f32_16x16x32_bf16 v[72:75], v[0:3], v[48:51], v[116:119]
	v_mfma_f32_16x16x32_bf16 v[112:115], v[8:11], v[56:59], v[72:75]
	v_mfma_f32_16x16x32_bf16 v[72:75], v[16:19], v[48:51], v[200:203]
	v_mfma_f32_16x16x32_bf16 v[116:119], v[24:27], v[56:59], v[72:75]
	v_mfma_f32_16x16x32_bf16 v[72:75], v[0:3], v[64:67], v[108:111]
	v_mfma_f32_16x16x32_bf16 v[104:107], v[8:11], v[166:169], v[72:75]
	v_mfma_f32_16x16x32_bf16 v[72:75], v[16:19], v[64:67], v[204:207]
	v_mfma_f32_16x16x32_bf16 v[108:111], v[24:27], v[166:169], v[72:75]
	v_mfma_f32_16x16x32_bf16 v[72:75], v[0:3], v[184:187], v[100:103]
	v_mfma_f32_16x16x32_bf16 v[96:99], v[8:11], v[188:191], v[72:75]
	v_mfma_f32_16x16x32_bf16 v[72:75], v[16:19], v[184:187], v[208:211]
	v_mfma_f32_16x16x32_bf16 v[100:103], v[24:27], v[188:191], v[72:75]
	s_setprio 0
	s_barrier
	ds_read_b128 v[130:133], v170
	ds_read_b128 v[196:199], v170 offset:1024
	ds_read_b128 v[200:203], v170 offset:2048
	ds_read_b128 v[204:207], v170 offset:3072
	s_waitcnt vmcnt(0)
	s_barrier
	s_waitcnt lgkmcnt(0)
	s_setprio 1
	s_waitcnt lgkmcnt(0)
	v_mfma_f32_16x16x32_bf16 v[72:75], v[130:133], v[32:35], v[92:95]
	v_mfma_f32_16x16x32_bf16 v[32:35], v[200:203], v[32:35], v[158:161]
	v_mfma_f32_16x16x32_bf16 v[92:95], v[204:207], v[40:43], v[32:35]
	v_mfma_f32_16x16x32_bf16 v[32:35], v[130:133], v[48:51], v[84:87]
	v_mfma_f32_16x16x32_bf16 v[80:83], v[196:199], v[56:59], v[32:35]
	v_mfma_f32_16x16x32_bf16 v[32:35], v[200:203], v[48:51], v[162:165]
	v_mfma_f32_16x16x32_bf16 v[84:87], v[204:207], v[56:59], v[32:35]
	v_mfma_f32_16x16x32_bf16 v[32:35], v[130:133], v[64:67], v[76:79]
	v_mfma_f32_16x16x32_bf16 v[88:91], v[196:199], v[40:43], v[72:75]
	v_mfma_f32_16x16x32_bf16 v[72:75], v[196:199], v[166:169], v[32:35]
	v_mfma_f32_16x16x32_bf16 v[32:35], v[200:203], v[64:67], v[172:175]
	v_mfma_f32_16x16x32_bf16 v[76:79], v[204:207], v[166:169], v[32:35]
	v_mfma_f32_16x16x32_bf16 v[32:35], v[130:133], v[184:187], v[68:71]
	v_mfma_f32_16x16x32_bf16 v[64:67], v[196:199], v[188:191], v[32:35]
	v_mfma_f32_16x16x32_bf16 v[32:35], v[200:203], v[184:187], v[176:179]
	v_mfma_f32_16x16x32_bf16 v[68:71], v[204:207], v[188:191], v[32:35]
	s_setprio 0
	s_barrier
	ds_read_b128 v[158:161], v153 offset:49152
	ds_read_b128 v[162:165], v153 offset:50176
	ds_read_b128 v[166:169], v152 offset:49152
	ds_read_b128 v[170:173], v152 offset:50176
	ds_read_b128 v[174:177], v150 offset:49152
	ds_read_b128 v[150:153], v150 offset:50176
	ds_read_b128 v[184:187], v149 offset:49152
	ds_read_b128 v[188:191], v149 offset:50176
	s_barrier
	s_waitcnt lgkmcnt(0)
	s_setprio 1
	s_waitcnt lgkmcnt(0)
	v_mfma_f32_16x16x32_bf16 v[32:35], v[0:3], v[158:161], v[60:63]
	v_mfma_f32_16x16x32_bf16 v[56:59], v[8:11], v[162:165], v[32:35]
	v_mfma_f32_16x16x32_bf16 v[32:35], v[16:19], v[158:161], v[212:215]
	v_mfma_f32_16x16x32_bf16 v[60:63], v[24:27], v[162:165], v[32:35]
	v_mfma_f32_16x16x32_bf16 v[32:35], v[0:3], v[166:169], v[52:55]
	v_mfma_f32_16x16x32_bf16 v[48:51], v[8:11], v[170:173], v[32:35]
	v_mfma_f32_16x16x32_bf16 v[32:35], v[16:19], v[166:169], v[216:219]
	v_mfma_f32_16x16x32_bf16 v[52:55], v[24:27], v[170:173], v[32:35]
	v_mfma_f32_16x16x32_bf16 v[32:35], v[0:3], v[174:177], v[44:47]
	v_mfma_f32_16x16x32_bf16 v[40:43], v[8:11], v[150:153], v[32:35]
	v_mfma_f32_16x16x32_bf16 v[32:35], v[16:19], v[174:177], v[220:223]
	v_mfma_f32_16x16x32_bf16 v[0:3], v[0:3], v[184:187], v[36:39]
	v_mfma_f32_16x16x32_bf16 v[44:47], v[24:27], v[150:153], v[32:35]
	v_mfma_f32_16x16x32_bf16 v[32:35], v[8:11], v[188:191], v[0:3]
	v_mfma_f32_16x16x32_bf16 v[0:3], v[16:19], v[184:187], v[134:137]
	v_mfma_f32_16x16x32_bf16 v[36:39], v[24:27], v[188:191], v[0:3]
	s_setprio 0
	s_setprio 1
	v_mfma_f32_16x16x32_bf16 v[0:3], v[130:133], v[158:161], v[28:31]
	v_mfma_f32_16x16x32_bf16 v[24:27], v[196:199], v[162:165], v[0:3]
	v_mfma_f32_16x16x32_bf16 v[0:3], v[200:203], v[158:161], v[138:141]
	v_mfma_f32_16x16x32_bf16 v[28:31], v[204:207], v[162:165], v[0:3]
	v_mfma_f32_16x16x32_bf16 v[0:3], v[130:133], v[166:169], v[20:23]
	v_mfma_f32_16x16x32_bf16 v[16:19], v[196:199], v[170:173], v[0:3]
	v_mfma_f32_16x16x32_bf16 v[0:3], v[200:203], v[166:169], v[142:145]
	v_mfma_f32_16x16x32_bf16 v[20:23], v[204:207], v[170:173], v[0:3]
	v_mfma_f32_16x16x32_bf16 v[0:3], v[130:133], v[174:177], v[12:15]
	v_mfma_f32_16x16x32_bf16 v[8:11], v[196:199], v[150:153], v[0:3]
	v_mfma_f32_16x16x32_bf16 v[0:3], v[200:203], v[174:177], v[154:157]
	v_mfma_f32_16x16x32_bf16 v[12:15], v[204:207], v[150:153], v[0:3]
	v_mfma_f32_16x16x32_bf16 v[0:3], v[130:133], v[184:187], v[4:7]
	v_mfma_f32_16x16x32_bf16 v[4:7], v[200:203], v[184:187], v[180:183]
	v_mfma_f32_16x16x32_bf16 v[0:3], v[196:199], v[188:191], v[0:3]
	v_mfma_f32_16x16x32_bf16 v[4:7], v[204:207], v[188:191], v[4:7]
	s_setprio 0
	v_readlane_b32 s24, v253, 16
	v_readlane_b32 s25, v253, 17
	s_andn2_b64 vcc, exec, s[24:25]
	s_barrier
	s_cbranch_vccnz .LBB0_638
	s_barrier
